# ret_out: first gate fragment load (and a touch of the second gate line) hoisted to right after the staging barrier so its first-touch latency overlaps the QK/PV/RS stage
# speedup vs baseline: 1.0322x; 1.0067x over previous
.LBB0_490:
	s_or_b64 exec, exec, s[0:1]
	v_lshlrev_b32_e32 v70, 7, v6
	v_lshlrev_b32_e32 v2, 3, v5
	v_ashrrev_i32_e32 v71, 31, v70
	v_and_b32_e32 v7, 56, v2
	v_bfe_u32 v13, v5, 3, 5
	v_lshlrev_b64 v[72:73], 1, v[70:71]
	v_lshlrev_b32_e32 v0, 3, v7
	v_mov_b32_e32 v1, v65
	v_or_b32_e32 v8, v3, v13
	v_lshl_add_u64 v[0:1], s[40:41], 0, v[0:1]
	v_lshlrev_b32_e32 v8, 9, v8
	v_mov_b32_e32 v9, v65
	v_lshl_add_u64 v[18:19], s[38:39], 0, v[72:73]
	v_lshlrev_b32_e32 v64, 1, v7
	v_lshl_add_u64 v[38:39], v[0:1], 0, v[8:9]
	v_lshl_add_u64 v[42:43], v[18:19], 0, v[64:65]
	v_add_u32_e32 v7, v68, v13
	global_load_dwordx4 v[8:11], v[38:39], off
	global_load_dwordx4 v[14:17], v[38:39], off offset:16
	global_load_dwordx4 v[18:21], v[38:39], off offset:32
	v_mad_i64_i32 v[34:35], s[0:1], v7, s57, v[42:43]
	global_load_dwordx4 v[22:25], v[34:35], off
	global_load_dwordx4 v[26:29], v[34:35], off offset:128
	global_load_dwordx4 v[30:33], v[34:35], off offset:1536
	s_nop 0
	global_load_dwordx4 v[34:37], v[34:35], off offset:1664
	s_nop 0
	global_load_dwordx4 v[38:41], v[38:39], off offset:48
	v_or_b32_sdwa v140, v5, s61 dst_sel:DWORD dst_unused:UNUSED_PAD src0_sel:BYTE_0 src1_sel:DWORD
	v_lshrrev_b32_e32 v141, 3, v140
	v_add_u32_e32 v142, v68, v141
	v_mad_i64_i32 v[134:135], s[0:1], v142, s57, v[42:43]
	v_or_b32_e32 v143, v3, v141
	v_lshlrev_b32_e32 v136, 9, v143
	v_mov_b32_e32 v137, v65
	v_lshl_add_u64 v[136:137], v[0:1], 0, v[136:137]
	global_load_dwordx4 v[160:163], v[134:135], off
	global_load_dwordx4 v[164:167], v[134:135], off offset:128
	global_load_dwordx4 v[168:171], v[134:135], off offset:1536
	global_load_dwordx4 v[172:175], v[134:135], off offset:1664
	global_load_dwordx4 v[176:179], v[136:137], off
	global_load_dwordx4 v[180:183], v[136:137], off offset:16
	global_load_dwordx4 v[184:187], v[136:137], off offset:32
	global_load_dwordx4 v[188:191], v[136:137], off offset:48
	v_bfe_u32 v140, v5, 4, 4
	v_add_u32_e32 v140, v68, v140
	v_mad_i64_i32 v[138:139], s[0:1], v140, s57, v[66:67]
	v_lshl_add_u64 v[138:139], v[138:139], 0, v[72:73]
	v_lshlrev_b32_e32 v140, 3, v5
	v_and_b32_e32 v140, 0x78, v140
	v_lshlrev_b32_e32 v140, 1, v140
	v_mov_b32_e32 v141, v65
	v_lshl_add_u64 v[138:139], v[138:139], 0, v[140:141]
	v_mov_b32_e32 v140, 0x1a000
	global_load_dwordx4 v[192:195], v[138:139], off offset:3072
	v_lshl_add_u64 v[138:139], v[138:139], 0, v[140:141]
	global_load_dwordx4 v[196:199], v[138:139], off offset:3072
	v_lshl_add_u64 v[138:139], v[138:139], 0, v[140:141]
	global_load_dwordx4 v[200:203], v[138:139], off offset:3072
	v_lshl_add_u64 v[138:139], v[138:139], 0, v[140:141]
	global_load_dwordx4 v[204:207], v[138:139], off offset:3072
	v_mul_u32_u24_e32 v7, 0x88, v13
	v_mad_i32_i24 v4, v4, s52, 0
	v_lshlrev_b32_e32 v7, 1, v7
	v_add3_u32 v7, v4, v7, v64
	s_add_i32 s2, s2, s84
	s_waitcnt vmcnt(12) lgkmcnt(0)
	v_mov_b32_e32 v44, v8
	v_mov_b32_e32 v45, v10
	v_mov_b32_e32 v10, v9
	v_mov_b32_e32 v8, v14
	v_mov_b32_e32 v9, v16
	v_mov_b32_e32 v16, v15
	v_mov_b32_e32 v14, v18
	v_mov_b32_e32 v15, v20
	v_mov_b32_e32 v20, v19
	v_lshlrev_b32_e32 v18, 16, v22
	v_and_b32_e32 v19, 0xffff0000, v22
	v_lshlrev_b32_e32 v22, 16, v23
	v_and_b32_e32 v23, 0xffff0000, v23
	v_lshlrev_b32_e32 v48, 16, v26
	v_and_b32_e32 v49, 0xffff0000, v26
	v_lshlrev_b32_e32 v26, 16, v27
	v_and_b32_e32 v27, 0xffff0000, v27
	v_lshlrev_b32_e32 v52, 16, v30
	v_and_b32_e32 v53, 0xffff0000, v30
	v_lshlrev_b32_e32 v30, 16, v31
	v_and_b32_e32 v31, 0xffff0000, v31
	v_lshlrev_b32_e32 v56, 16, v34
	v_and_b32_e32 v57, 0xffff0000, v34
	v_lshlrev_b32_e32 v34, 16, v35
	v_and_b32_e32 v35, 0xffff0000, v35
	v_pk_mul_f32 v[76:77], v[16:17], v[26:27]
	v_pk_mul_f32 v[84:85], v[16:17], v[22:23]
	v_pk_mul_f32 v[86:87], v[16:17], v[34:35]
	v_pk_mul_f32 v[16:17], v[16:17], v[30:31]
	v_lshlrev_b32_e32 v46, 16, v24
	v_and_b32_e32 v47, 0xffff0000, v24
	v_lshlrev_b32_e32 v50, 16, v28
	v_and_b32_e32 v51, 0xffff0000, v28
	v_pk_mul_f32 v[60:61], v[10:11], v[48:49]
	v_pk_mul_f32 v[62:63], v[10:11], v[18:19]
	v_pk_mul_f32 v[74:75], v[10:11], v[56:57]
	v_pk_mul_f32 v[10:11], v[10:11], v[52:53]
	v_pk_fma_f32 v[22:23], v[8:9], v[22:23], v[76:77] neg_lo:[0,0,1] neg_hi:[0,0,1]
	v_pk_fma_f32 v[26:27], v[8:9], v[26:27], v[84:85]
	v_pk_fma_f32 v[30:31], v[8:9], v[30:31], v[86:87] neg_lo:[0,0,1] neg_hi:[0,0,1]
	v_pk_fma_f32 v[8:9], v[8:9], v[34:35], v[16:17]
	v_lshlrev_b32_e32 v58, 16, v36
	v_and_b32_e32 v59, 0xffff0000, v36
	v_pk_mul_f32 v[88:89], v[20:21], v[50:51]
	v_pk_fma_f32 v[18:19], v[44:45], v[18:19], v[60:61] neg_lo:[0,0,1] neg_hi:[0,0,1]
	v_pk_fma_f32 v[48:49], v[44:45], v[48:49], v[62:63]
	v_pk_fma_f32 v[52:53], v[44:45], v[52:53], v[74:75] neg_lo:[0,0,1] neg_hi:[0,0,1]
	v_pk_fma_f32 v[10:11], v[44:45], v[56:57], v[10:11]
	v_pk_mul_f32 v[44:45], v[8:9], s[44:45] op_sel_hi:[1,0]
	v_pk_mul_f32 v[8:9], v[20:21], v[46:47]
	v_lshlrev_b32_e32 v54, 16, v32
	v_and_b32_e32 v55, 0xffff0000, v32
	v_pk_mul_f32 v[34:35], v[10:11], s[44:45] op_sel_hi:[1,0]
	v_pk_fma_f32 v[10:11], v[14:15], v[46:47], v[88:89] neg_lo:[0,0,1] neg_hi:[0,0,1]
	v_pk_fma_f32 v[46:47], v[14:15], v[50:51], v[8:9]
	v_pk_mul_f32 v[8:9], v[20:21], v[58:59]
	v_lshlrev_b32_e32 v28, 16, v29
	v_pk_fma_f32 v[8:9], v[14:15], v[54:55], v[8:9] neg_lo:[0,0,1] neg_hi:[0,0,1]
	v_and_b32_e32 v29, 0xffff0000, v29
	v_pk_mul_f32 v[50:51], v[8:9], s[44:45] op_sel_hi:[1,0]
	v_pk_mul_f32 v[8:9], v[20:21], v[54:55]
	v_lshlrev_b32_e32 v24, 16, v25
	v_pk_fma_f32 v[8:9], v[14:15], v[58:59], v[8:9]
	v_and_b32_e32 v25, 0xffff0000, v25
	v_pk_mul_f32 v[14:15], v[8:9], s[44:45] op_sel_hi:[1,0]
	v_mov_b32_e32 v9, v40
	v_mov_b32_e32 v40, v39
	v_mov_b32_e32 v8, v38
	v_pk_mul_f32 v[20:21], v[40:41], v[28:29]
	v_lshlrev_b32_e32 v36, 16, v37
	v_and_b32_e32 v37, 0xffff0000, v37
	v_pk_fma_f32 v[20:21], v[8:9], v[24:25], v[20:21] neg_lo:[0,0,1] neg_hi:[0,0,1]
	v_pk_mul_f32 v[24:25], v[40:41], v[24:25]
	v_lshlrev_b32_e32 v32, 16, v33
	v_and_b32_e32 v33, 0xffff0000, v33
	v_pk_fma_f32 v[24:25], v[8:9], v[28:29], v[24:25]
	v_pk_mul_f32 v[28:29], v[40:41], v[36:37]
	v_cvt_pk_bf16_f32 v10, v10, v11
	v_pk_fma_f32 v[28:29], v[8:9], v[32:33], v[28:29] neg_lo:[0,0,1] neg_hi:[0,0,1]
	v_pk_mul_f32 v[32:33], v[40:41], v[32:33]
	v_cvt_pk_bf16_f32 v11, v20, v21
	v_pk_fma_f32 v[8:9], v[8:9], v[36:37], v[32:33]
	v_pk_mul_f32 v[16:17], v[52:53], s[44:45] op_sel_hi:[1,0]
	v_pk_mul_f32 v[32:33], v[8:9], s[44:45] op_sel_hi:[1,0]
	v_cvt_pk_bf16_f32 v8, v18, v19
	v_cvt_pk_bf16_f32 v9, v22, v23
	v_pk_mul_f32 v[30:31], v[30:31], s[44:45] op_sel_hi:[1,0]
	v_pk_mul_f32 v[28:29], v[28:29], s[44:45] op_sel_hi:[1,0]
	ds_write_b128 v7, v[8:11]
	v_cvt_pk_bf16_f32 v8, v48, v49
	v_cvt_pk_bf16_f32 v9, v26, v27
	v_cvt_pk_bf16_f32 v10, v46, v47
	v_cvt_pk_bf16_f32 v11, v24, v25
	ds_write_b128 v7, v[8:11] offset:128
	v_cvt_pk_bf16_f32 v8, v16, v17
	v_cvt_pk_bf16_f32 v9, v30, v31
	v_cvt_pk_bf16_f32 v10, v50, v51
	v_cvt_pk_bf16_f32 v11, v28, v29
	ds_write_b128 v7, v[8:11] offset:17408
	v_cvt_pk_bf16_f32 v8, v34, v35
	v_cvt_pk_bf16_f32 v9, v44, v45
	v_cvt_pk_bf16_f32 v10, v14, v15
	v_cvt_pk_bf16_f32 v11, v32, v33
	ds_write_b128 v7, v[8:11] offset:17536
	v_or_b32_sdwa v7, v5, s61 dst_sel:DWORD dst_unused:UNUSED_PAD src0_sel:BYTE_0 src1_sel:DWORD
	v_lshrrev_b32_e32 v13, 3, v7
	v_add_u32_e32 v8, v68, v13
	v_or_b32_e32 v3, v3, v13
	v_mad_i64_i32 v[22:23], s[0:1], v8, s57, v[42:43]
	v_lshlrev_b32_e32 v26, 9, v3
	v_mov_b32_e32 v27, v65
	s_nop 0
	v_lshl_add_u64 v[0:1], v[0:1], 0, v[26:27]
	v_mul_u32_u24_e32 v3, 0x88, v13
	v_lshlrev_b32_e32 v3, 1, v3
	v_add3_u32 v3, v4, v3, v64
	v_lshrrev_b32_e32 v7, 4, v7
	s_waitcnt vmcnt(4) lgkmcnt(0)
	v_mov_b64_e32 v[8:9], v[160:161]
	v_mov_b64_e32 v[10:11], v[162:163]
	v_mov_b64_e32 v[14:15], v[164:165]
	v_mov_b64_e32 v[16:17], v[166:167]
	v_mov_b64_e32 v[18:19], v[168:169]
	v_mov_b64_e32 v[20:21], v[170:171]
	v_mov_b64_e32 v[22:23], v[172:173]
	v_mov_b64_e32 v[24:25], v[174:175]
	v_mov_b64_e32 v[26:27], v[176:177]
	v_mov_b64_e32 v[28:29], v[178:179]
	v_mov_b64_e32 v[30:31], v[180:181]
	v_mov_b64_e32 v[32:33], v[182:183]
	v_mov_b64_e32 v[34:35], v[184:185]
	v_mov_b64_e32 v[36:37], v[186:187]
	v_mov_b64_e32 v[38:39], v[188:189]
	v_mov_b64_e32 v[40:41], v[190:191]
	v_lshlrev_b32_e32 v0, 16, v8
	v_lshlrev_b32_e32 v44, 16, v14
	v_and_b32_e32 v45, 0xffff0000, v14
	v_mov_b32_e32 v57, v28
	v_mov_b32_e32 v28, v27
	v_and_b32_e32 v1, 0xffff0000, v8
	v_mov_b32_e32 v56, v26
	v_pk_mul_f32 v[26:27], v[28:29], v[44:45]
	v_lshlrev_b32_e32 v52, 16, v22
	v_and_b32_e32 v53, 0xffff0000, v22
	v_pk_fma_f32 v[26:27], v[56:57], v[0:1], v[26:27] neg_lo:[0,0,1] neg_hi:[0,0,1]
	v_pk_mul_f32 v[0:1], v[28:29], v[0:1]
	v_lshlrev_b32_e32 v48, 16, v18
	v_and_b32_e32 v49, 0xffff0000, v18
	v_pk_fma_f32 v[0:1], v[56:57], v[44:45], v[0:1]
	v_pk_mul_f32 v[44:45], v[28:29], v[52:53]
	v_lshlrev_b32_e32 v14, 16, v15
	v_and_b32_e32 v15, 0xffff0000, v15
	v_pk_fma_f32 v[44:45], v[56:57], v[48:49], v[44:45] neg_lo:[0,0,1] neg_hi:[0,0,1]
	v_pk_mul_f32 v[28:29], v[28:29], v[48:49]
	v_mov_b32_e32 v49, v32
	v_mov_b32_e32 v32, v31
	v_lshlrev_b32_e32 v8, 16, v9
	v_and_b32_e32 v9, 0xffff0000, v9
	v_mov_b32_e32 v48, v30
	v_pk_mul_f32 v[30:31], v[32:33], v[14:15]
	v_lshlrev_b32_e32 v22, 16, v23
	v_and_b32_e32 v23, 0xffff0000, v23
	v_pk_fma_f32 v[30:31], v[48:49], v[8:9], v[30:31] neg_lo:[0,0,1] neg_hi:[0,0,1]
	v_pk_mul_f32 v[8:9], v[32:33], v[8:9]
	v_lshlrev_b32_e32 v18, 16, v19
	v_and_b32_e32 v19, 0xffff0000, v19
	v_pk_fma_f32 v[14:15], v[48:49], v[14:15], v[8:9]
	v_pk_mul_f32 v[8:9], v[32:33], v[22:23]
	v_pk_fma_f32 v[28:29], v[56:57], v[52:53], v[28:29]
	v_pk_fma_f32 v[8:9], v[48:49], v[18:19], v[8:9] neg_lo:[0,0,1] neg_hi:[0,0,1]
	v_lshlrev_b32_e32 v42, 16, v10
	v_pk_mul_f32 v[52:53], v[8:9], s[44:45] op_sel_hi:[1,0]
	v_pk_mul_f32 v[8:9], v[32:33], v[18:19]
	v_and_b32_e32 v43, 0xffff0000, v10
	v_pk_fma_f32 v[8:9], v[48:49], v[22:23], v[8:9]
	v_lshlrev_b32_e32 v46, 16, v16
	v_and_b32_e32 v47, 0xffff0000, v16
	v_lshlrev_b32_e32 v50, 16, v20
	v_and_b32_e32 v51, 0xffff0000, v20
	v_lshlrev_b32_e32 v54, 16, v24
	v_and_b32_e32 v55, 0xffff0000, v24
	v_pk_mul_f32 v[18:19], v[8:9], s[44:45] op_sel_hi:[1,0]
	v_mov_b32_e32 v9, v36
	v_mov_b32_e32 v36, v35
	v_mov_b32_e32 v8, v34
	v_pk_mul_f32 v[22:23], v[36:37], v[46:47]
	v_pk_mul_f32 v[32:33], v[36:37], v[42:43]
	v_pk_mul_f32 v[34:35], v[36:37], v[54:55]
	v_pk_mul_f32 v[36:37], v[36:37], v[50:51]
	v_pk_fma_f32 v[22:23], v[8:9], v[42:43], v[22:23] neg_lo:[0,0,1] neg_hi:[0,0,1]
	v_pk_fma_f32 v[32:33], v[8:9], v[46:47], v[32:33]
	v_pk_fma_f32 v[34:35], v[8:9], v[50:51], v[34:35] neg_lo:[0,0,1] neg_hi:[0,0,1]
	v_pk_fma_f32 v[8:9], v[8:9], v[54:55], v[36:37]
	v_lshlrev_b32_e32 v16, 16, v17
	v_and_b32_e32 v17, 0xffff0000, v17
	v_pk_mul_f32 v[36:37], v[8:9], s[44:45] op_sel_hi:[1,0]
	v_mov_b32_e32 v9, v40
	v_mov_b32_e32 v40, v39
	v_lshlrev_b32_e32 v10, 16, v11
	v_and_b32_e32 v11, 0xffff0000, v11
	v_mov_b32_e32 v8, v38
	v_pk_mul_f32 v[38:39], v[40:41], v[16:17]
	v_lshlrev_b32_e32 v24, 16, v25
	v_and_b32_e32 v25, 0xffff0000, v25
	v_pk_fma_f32 v[38:39], v[8:9], v[10:11], v[38:39] neg_lo:[0,0,1] neg_hi:[0,0,1]
	v_pk_mul_f32 v[10:11], v[40:41], v[10:11]
	v_lshlrev_b32_e32 v20, 16, v21
	v_and_b32_e32 v21, 0xffff0000, v21
	v_pk_fma_f32 v[16:17], v[8:9], v[16:17], v[10:11]
	v_pk_mul_f32 v[10:11], v[40:41], v[24:25]
	v_pk_mul_f32 v[44:45], v[44:45], s[44:45] op_sel_hi:[1,0]
	v_pk_fma_f32 v[10:11], v[8:9], v[20:21], v[10:11] neg_lo:[0,0,1] neg_hi:[0,0,1]
	v_pk_mul_f32 v[34:35], v[34:35], s[44:45] op_sel_hi:[1,0]
	v_pk_mul_f32 v[42:43], v[10:11], s[44:45] op_sel_hi:[1,0]
	v_pk_mul_f32 v[10:11], v[40:41], v[20:21]
	v_pk_mul_f32 v[28:29], v[28:29], s[44:45] op_sel_hi:[1,0]
	v_pk_fma_f32 v[8:9], v[8:9], v[24:25], v[10:11]
	v_cvt_pk_bf16_f32 v10, v22, v23
	v_pk_mul_f32 v[20:21], v[8:9], s[44:45] op_sel_hi:[1,0]
	v_cvt_pk_bf16_f32 v8, v26, v27
	v_cvt_pk_bf16_f32 v9, v30, v31
	v_cvt_pk_bf16_f32 v11, v38, v39
	ds_write_b128 v3, v[8:11]
	v_cvt_pk_bf16_f32 v8, v0, v1
	v_cvt_pk_bf16_f32 v9, v14, v15
	v_cvt_pk_bf16_f32 v10, v32, v33
	v_cvt_pk_bf16_f32 v11, v16, v17
	ds_write_b128 v3, v[8:11] offset:128
	v_cvt_pk_bf16_f32 v8, v44, v45
	v_cvt_pk_bf16_f32 v9, v52, v53
	v_cvt_pk_bf16_f32 v10, v34, v35
	v_cvt_pk_bf16_f32 v11, v42, v43
	ds_write_b128 v3, v[8:11] offset:17408
	v_cvt_pk_bf16_f32 v8, v28, v29
	v_cvt_pk_bf16_f32 v9, v18, v19
	v_cvt_pk_bf16_f32 v10, v36, v37
	v_cvt_pk_bf16_f32 v11, v20, v21
	ds_write_b128 v3, v[8:11] offset:17536
	v_bfe_u32 v9, v5, 4, 4
	v_add_u32_e32 v10, v68, v9
	v_and_b32_e32 v8, 0x78, v2
	v_mad_i64_i32 v[0:1], s[0:1], v10, s57, v[66:67]
	v_lshl_add_u64 v[0:1], v[0:1], 0, v[72:73]
	v_lshlrev_b32_e32 v64, 1, v8
	v_lshl_add_u64 v[0:1], v[0:1], 0, v[64:65]
	v_mul_u32_u24_e32 v8, 0x48, v8
	v_lshlrev_b32_e32 v11, 1, v8
	v_lshlrev_b32_e32 v9, 1, v9
	v_add_u32_e32 v14, v4, v11
	v_add3_u32 v13, v4, v9, v11
	v_add_u32_e32 v15, v14, v9
	v_add_u32_e32 v8, 32, v10
	v_mad_i64_i32 v[8:9], s[0:1], v8, s57, v[66:67]
	v_lshl_add_u64 v[8:9], v[8:9], 0, v[72:73]
	v_lshl_add_u64 v[8:9], v[8:9], 0, v[64:65]
	v_and_b32_e32 v20, 15, v5
	v_bfe_u32 v21, v5, 4, 2
	v_lshrrev_b32_e32 v5, 2, v5
	v_and_or_b32 v76, v5, 48, v20
	v_lshlrev_b32_e32 v5, 2, v21
	v_lshlrev_b32_e32 v74, 4, v21
	v_sub_u32_e32 v69, v76, v5
	v_add_u32_e32 v16, -2, v69
	v_cvt_f32_i32_e32 v16, v16
	v_add_u32_e32 v17, -3, v69
	v_subrev_u32_e32 v22, 17, v69
	v_subrev_u32_e32 v23, 18, v69
	v_subrev_u32_e32 v24, 19, v69
	v_subrev_u32_e32 v25, 33, v69
	v_cvt_f32_i32_e32 v17, v17
	v_cvt_f32_i32_e32 v22, v22
	v_cvt_f32_i32_e32 v23, v23
	v_cvt_f32_i32_e32 v24, v24
	v_cvt_f32_i32_e32 v25, v25
	v_subrev_u32_e32 v26, 34, v69
	v_subrev_u32_e32 v27, 35, v69
	v_cvt_f32_i32_e32 v26, v26
	v_cvt_f32_i32_e32 v34, v27
	v_subrev_u32_e32 v28, 49, v69
	s_add_i32 s45, s45, s48
	s_cmpk_gt_i32 s2, 0x62f
	s_waitcnt vmcnt(3) lgkmcnt(0)
	v_mov_b64_e32 v[0:1], v[192:193]
	v_mov_b64_e32 v[2:3], v[194:195]
	ds_write_b16 v13, v0 offset:34816
	ds_write_b16_d16_hi v15, v0 offset:34960
	ds_write_b16 v13, v1 offset:35104
	ds_write_b16_d16_hi v15, v1 offset:35248
	ds_write_b16 v13, v2 offset:35392
	ds_write_b16_d16_hi v15, v2 offset:35536
	ds_write_b16 v13, v3 offset:35680
	ds_write_b16_d16_hi v15, v3 offset:35824
	v_add_u32_e32 v0, v68, v7
	v_mad_i64_i32 v[0:1], s[0:1], v0, s57, v[66:67]
	v_lshl_add_u64 v[0:1], v[0:1], 0, v[72:73]
	v_lshl_add_u64 v[0:1], v[0:1], 0, v[64:65]
	v_lshlrev_b32_e32 v7, 1, v7
	v_add3_u32 v11, v4, v7, v11
	v_add_u32_e32 v7, v14, v7
	s_waitcnt vmcnt(2) lgkmcnt(0)
	v_mov_b64_e32 v[0:1], v[196:197]
	v_mov_b64_e32 v[2:3], v[198:199]
	ds_write_b16 v11, v0 offset:34816
	ds_write_b16_d16_hi v7, v0 offset:34960
	ds_write_b16 v11, v1 offset:35104
	ds_write_b16_d16_hi v7, v1 offset:35248
	ds_write_b16 v11, v2 offset:35392
	ds_write_b16_d16_hi v7, v2 offset:35536
	ds_write_b16 v11, v3 offset:35680
	ds_write_b16_d16_hi v7, v3 offset:35824
	v_cvt_f32_i32_e32 v8, v6
	v_add_u32_e32 v6, 48, v10
	v_mad_i64_i32 v[6:7], s[0:1], v6, s57, v[66:67]
	v_lshl_add_u64 v[6:7], v[6:7], 0, v[72:73]
	v_lshl_add_u64 v[6:7], v[6:7], 0, v[64:65]
	s_waitcnt vmcnt(1) lgkmcnt(0)
	v_mov_b64_e32 v[0:1], v[200:201]
	v_mov_b64_e32 v[2:3], v[202:203]
	ds_write_b16 v13, v0 offset:34880
	ds_write_b16_d16_hi v15, v0 offset:35024
	ds_write_b16 v13, v1 offset:35168
	ds_write_b16_d16_hi v15, v1 offset:35312
	ds_write_b16 v13, v2 offset:35456
	ds_write_b16_d16_hi v15, v2 offset:35600
	ds_write_b16 v13, v3 offset:35744
	ds_write_b16_d16_hi v15, v3 offset:35888
	v_sub_f32_e32 v8, 0xc0a00000, v8
	v_cmp_gt_f32_e32 vcc, s53, v8
	v_add_u32_e32 v9, v4, v74
	v_xad_u32 v10, v5, -1, v76
	v_cndmask_b32_e32 v29, 0, v78, vcc
	v_add_f32_e32 v8, v8, v29
	v_exp_f32_e32 v6, v8
	v_cndmask_b32_e32 v7, 0, v79, vcc
	v_mad_u32_u24 v18, v76, s62, v9
	v_mad_u32_u24 v19, v20, s62, v9
	v_ldexp_f32 v6, v6, v7
	v_sub_f32_e32 v6, 1.0, v6
	v_cmp_gt_f32_e32 vcc, s54, v6
	v_cvt_f32_i32_e32 v9, v69
	v_cvt_f32_i32_e32 v10, v10
	v_cndmask_b32_e64 v7, 0, 32, vcc
	v_ldexp_f32 v6, v6, v7
	v_log_f32_e32 v6, v6
	v_cndmask_b32_e32 v7, 0, v80, vcc
	v_or_b32_e32 v14, 32, v5
	s_waitcnt vmcnt(0) lgkmcnt(0)
	v_mov_b64_e32 v[0:1], v[204:205]
	v_mov_b64_e32 v[2:3], v[206:207]
	ds_write_b16 v13, v0 offset:34912
	ds_write_b16_d16_hi v15, v0 offset:35056
	ds_write_b16 v13, v1 offset:35200
	ds_write_b16_d16_hi v15, v1 offset:35344
	ds_write_b16 v13, v2 offset:35488
	ds_write_b16_d16_hi v15, v2 offset:35632
	ds_write_b16 v13, v3 offset:35776
	ds_write_b16_d16_hi v15, v3 offset:35920
	v_mul_f32_e32 v8, 0x3f317217, v6
	v_fma_f32 v8, v6, s55, -v8
	v_fmac_f32_e32 v8, 0x3377d1cf, v6
	v_fmac_f32_e32 v8, 0x3f317217, v6
	v_cmp_lt_f32_e64 vcc, |v6|, s56
	s_waitcnt lgkmcnt(0)
	s_barrier
	v_add_u32_e32 v254, v68, v76
	v_mul_u32_u24_e32 v254, 0x1a00, v254
	v_lshrrev_b32_e32 v253, 1, v74
	v_add3_u32 v254, v254, v72, v253
	v_add_u32_e32 v254, s46, v254
	global_load_dwordx2 v[252:253], v254, s[38:39]
	global_load_dword v149, v254, s[38:39] offset:128
	v_cndmask_b32_e32 v6, v6, v8, vcc
	v_sub_f32_e32 v6, v6, v7
	ds_read_b128 v[0:3], v19 offset:17408
	v_sub_u32_e32 v14, v76, v14
	v_mul_f32_e32 v83, 0x3fb8aa3b, v6
	v_cvt_f32_i32_e32 v14, v14
	v_mul_f32_e64 v6, |v9|, v83
	v_mul_f32_e64 v7, |v10|, v83
	v_mul_f32_e64 v8, |v16|, v83
	v_cmp_gt_f32_e32 vcc, s53, v6
	v_cmp_gt_f32_e64 s[0:1], s53, v7
	v_cmp_gt_f32_e64 s[4:5], s53, v8
	v_or_b32_e32 v11, 16, v5
	v_or_b32_e32 v5, 48, v5
	v_cndmask_b32_e32 v6, 0, v78, vcc
	v_cndmask_b32_e64 v7, 0, v78, s[0:1]
	v_cndmask_b32_e64 v8, 0, v78, s[4:5]
	v_sub_u32_e32 v11, v76, v11
	v_sub_u32_e32 v5, v76, v5
	v_fma_f32 v42, |v9|, v83, v6
	v_fma_f32 v10, |v10|, v83, v7
	v_fma_f32 v43, |v16|, v83, v8
	ds_read_b128 v[56:59], v18
	ds_read_b128 v[6:9], v19 offset:21760
	v_cvt_f32_i32_e32 v11, v11
	v_cvt_f32_i32_e32 v5, v5
	v_mul_f32_e64 v27, |v17|, v83
	v_mul_f32_e64 v29, |v22|, v83
	v_mul_f32_e64 v30, |v23|, v83
	v_mul_f32_e64 v31, |v24|, v83
	v_mul_f32_e64 v32, |v14|, v83
	v_mul_f32_e64 v33, |v25|, v83
	v_cmp_gt_f32_e64 s[6:7], s53, v27
	v_cmp_gt_f32_e64 s[10:11], s53, v29
	v_cmp_gt_f32_e64 s[12:13], s53, v30
	v_cmp_gt_f32_e64 s[14:15], s53, v31
	v_cmp_gt_f32_e64 s[16:17], s53, v32
	v_cmp_gt_f32_e64 s[18:19], s53, v33
	v_cndmask_b32_e64 v27, 0, v78, s[6:7]
	v_cndmask_b32_e64 v29, 0, v78, s[10:11]
	v_cndmask_b32_e64 v30, 0, v78, s[12:13]
	v_cndmask_b32_e64 v31, 0, v78, s[14:15]
	v_cndmask_b32_e64 v32, 0, v78, s[16:17]
	v_cndmask_b32_e64 v33, 0, v78, s[18:19]
	v_fma_f32 v44, |v17|, v83, v27
	v_fma_f32 v45, |v22|, v83, v29
	v_fma_f32 v48, |v23|, v83, v30
	v_fma_f32 v49, |v24|, v83, v31
	v_fma_f32 v50, |v14|, v83, v32
	v_fma_f32 v13, |v25|, v83, v33
	ds_read_b128 v[60:63], v18 offset:64
	ds_read_b128 v[14:17], v19 offset:17472
	ds_read_b128 v[22:25], v19 offset:26112
	s_waitcnt lgkmcnt(4)
	v_mfma_f32_16x16x32_bf16 v[0:3], v[0:3], v[56:59], 0
	v_cvt_f32_i32_e32 v64, v28
	v_mul_f32_e64 v28, |v11|, v83
	v_mul_f32_e64 v35, |v26|, v83
	v_mul_f32_e64 v36, |v34|, v83
	v_mul_f32_e64 v37, |v5|, v83
	v_cmp_gt_f32_e64 s[8:9], s53, v28
	v_cmp_gt_f32_e64 s[20:21], s53, v35
	v_cmp_gt_f32_e64 s[22:23], s53, v36
	v_cmp_gt_f32_e64 s[24:25], s53, v37
	v_cndmask_b32_e64 v28, 0, v78, s[8:9]
	v_cndmask_b32_e64 v35, 0, v78, s[20:21]
	v_cndmask_b32_e64 v36, 0, v78, s[22:23]
	v_cndmask_b32_e64 v38, 0, v78, s[24:25]
	v_fma_f32 v11, |v11|, v83, v28
	v_fma_f32 v91, |v26|, v83, v35
	ds_read_b128 v[26:29], v19 offset:21824
	ds_read_b128 v[30:33], v19 offset:30464
	v_fma_f32 v93, |v34|, v83, v36
	ds_read_b128 v[34:37], v19 offset:26176
	v_fma_f32 v5, |v5|, v83, v38
	ds_read_b128 v[38:41], v19 offset:30528
	s_waitcnt lgkmcnt(5)
	v_mfma_f32_16x16x32_bf16 v[0:3], v[14:17], v[60:63], v[0:3]
	ds_read_b128 v[14:17], v19 offset:17536
	v_exp_f32_e32 v102, v48
	v_exp_f32_e32 v103, v49
	v_mfma_f32_16x16x32_bf16 v[6:9], v[6:9], v[56:59], 0
	v_exp_f32_e32 v104, v50
	v_exp_f32_e32 v96, v42
	v_exp_f32_e32 v97, v10
	s_waitcnt lgkmcnt(5)
	v_mfma_f32_16x16x32_bf16 v[22:25], v[22:25], v[56:59], 0
	v_exp_f32_e32 v98, v43
	v_exp_f32_e32 v99, v44
	v_exp_f32_e32 v101, v45
	s_waitcnt lgkmcnt(3)
	v_mfma_f32_16x16x32_bf16 v[30:33], v[30:33], v[56:59], 0
	v_mul_f32_e64 v75, |v64|, v83
	v_cndmask_b32_e32 v46, 0, v79, vcc
	v_cndmask_b32_e64 v47, 0, v79, s[0:1]
	v_mfma_f32_16x16x32_bf16 v[6:9], v[26:29], v[60:63], v[6:9]
	ds_read_b128 v[52:55], v18 offset:128
	ds_read_b128 v[26:29], v19 offset:21888
	v_exp_f32_e32 v100, v11
	v_ldexp_f32 v10, v96, v46
	s_waitcnt lgkmcnt(4)
	v_mfma_f32_16x16x32_bf16 v[22:25], v[34:37], v[60:63], v[22:25]
	v_ldexp_f32 v11, v97, v47
	v_cmp_gt_f32_e32 vcc, s53, v75
	v_cndmask_b32_e64 v77, 0, v79, s[4:5]
	s_waitcnt lgkmcnt(3)
	v_mfma_f32_16x16x32_bf16 v[30:33], v[38:41], v[60:63], v[30:33]
	ds_read_b128 v[48:51], v18 offset:192
	ds_read_b128 v[34:37], v19 offset:17600
	ds_read_b128 v[38:41], v19 offset:26240
	v_cndmask_b32_e64 v84, 0, v79, s[6:7]
	v_ldexp_f32 v18, v98, v77
	s_waitcnt lgkmcnt(4)
	v_mfma_f32_16x16x32_bf16 v[0:3], v[14:17], v[52:55], v[0:3]
	ds_read_b128 v[14:17], v19 offset:21952
	ds_read_b128 v[42:45], v19 offset:30592
	v_exp_f32_e32 v13, v13
	v_exp_f32_e32 v91, v91
	s_waitcnt lgkmcnt(3)
	v_mfma_f32_16x16x32_bf16 v[0:3], v[34:37], v[48:51], v[0:3]
	v_exp_f32_e32 v93, v93
	v_cndmask_b32_e64 v90, 0, v79, s[18:19]
	v_cndmask_b32_e64 v89, 0, v79, s[16:17]
	v_mfma_f32_16x16x32_bf16 v[6:9], v[26:29], v[52:55], v[6:9]
	ds_read_b128 v[26:29], v19 offset:26304
	s_nop 2
	v_pk_mul_f32 v[10:11], v[10:11], v[0:1]
	v_cndmask_b32_e32 v0, 0, v78, vcc
	v_fma_f32 v0, |v64|, v83, v0
	v_subrev_u32_e32 v1, 50, v69
	s_waitcnt lgkmcnt(3)
	v_mfma_f32_16x16x32_bf16 v[22:25], v[38:41], v[52:55], v[22:25]
	v_exp_f32_e32 v0, v0
	v_cvt_f32_i32_e32 v1, v1
	ds_read_b128 v[38:41], v19 offset:30656
	v_ldexp_f32 v19, v99, v84
	v_pk_mul_f32 v[18:19], v[18:19], v[2:3]
	v_cndmask_b32_e32 v2, 0, v79, vcc
	s_waitcnt lgkmcnt(3)
	v_mfma_f32_16x16x32_bf16 v[6:9], v[14:17], v[48:51], v[6:9]
	v_lshlrev_b32_e32 v64, 3, v21
	v_cndmask_b32_e64 v92, 0, v79, s[20:21]
	v_cndmask_b32_e64 v94, 0, v79, s[22:23]
	s_waitcnt lgkmcnt(1)
	v_mfma_f32_16x16x32_bf16 v[14:17], v[26:29], v[48:51], v[22:25]
	v_ldexp_f32 v29, v0, v2
	v_mul_f32_e64 v0, |v1|, v83
	v_cmp_gt_f32_e32 vcc, s53, v0
	v_mfma_f32_16x16x32_bf16 v[30:33], v[42:45], v[52:55], v[30:33]
	v_ldexp_f32 v43, v13, v90
	v_cndmask_b32_e32 v0, 0, v78, vcc
	v_fma_f32 v13, |v1|, v83, v0
	v_mul_u32_u24_e32 v0, 0x90, v20
	v_add3_u32 v21, v4, v64, v0
	v_exp_f32_e32 v5, v5
	v_ldexp_f32 v42, v104, v89
	v_ldexp_f32 v26, v91, v92
	v_ldexp_f32 v27, v93, v94
	v_add_u32_e32 v92, 0x9800, v21
	v_pk_mul_f32 v[46:47], v[42:43], v[14:15]
	v_pk_mul_f32 v[90:91], v[26:27], v[16:17]
	ds_read2_b64 v[14:17], v92 offset0:64 offset1:68
	v_exp_f32_e32 v13, v13
	v_cndmask_b32_e64 v95, 0, v79, s[24:25]
	v_ldexp_f32 v28, v5, v95
	v_cvt_pk_bf16_f32 v5, v18, v19
	v_cndmask_b32_e32 v18, 0, v79, vcc
	v_ldexp_f32 v18, v13, v18
	v_subrev_u32_e32 v13, 51, v69
	v_cndmask_b32_e64 v85, 0, v79, s[8:9]
	v_cndmask_b32_e64 v86, 0, v79, s[10:11]
	v_cndmask_b32_e64 v87, 0, v79, s[12:13]
	v_cndmask_b32_e64 v88, 0, v79, s[14:15]
	s_waitcnt lgkmcnt(1)
	v_mfma_f32_16x16x32_bf16 v[22:25], v[38:41], v[48:51], v[30:33]
	v_cvt_f32_i32_e32 v13, v13
	v_ldexp_f32 v34, v100, v85
	v_ldexp_f32 v35, v101, v86
	v_ldexp_f32 v36, v102, v87
	v_ldexp_f32 v37, v103, v88
	v_pk_mul_f32 v[6:7], v[34:35], v[6:7]
	v_pk_mul_f32 v[30:31], v[36:37], v[8:9]
	v_add_u32_e32 v75, 0x8800, v21
	v_cvt_pk_bf16_f32 v4, v10, v11
	v_add_u32_e32 v77, 0x9000, v21
	v_cvt_pk_bf16_f32 v6, v6, v7
	v_cvt_pk_bf16_f32 v7, v30, v31
	v_add_u32_e32 v93, 0xa000, v21
	v_add_u32_e32 v94, 0xa800, v21
	v_add_u32_e32 v69, 0xb000, v21
	v_add_u32_e32 v95, 0xb800, v21
	v_add_u32_e32 v96, 0xc000, v21
	v_pk_mul_f32 v[22:23], v[28:29], v[22:23]
	ds_read2_b64 v[0:3], v75 offset1:4
	ds_read2_b64 v[8:11], v77 offset0:32 offset1:36
	ds_read2_b64 v[26:29], v93 offset0:96 offset1:100
	ds_read2_b64 v[30:33], v94 offset0:128 offset1:132
	s_waitcnt lgkmcnt(4)
	v_mfma_f32_16x16x32_bf16 v[34:37], v[14:17], v[4:7], 0
	ds_read2_b64 v[14:17], v69 offset0:160 offset1:164
	v_mul_f32_e64 v19, |v13|, v83
	ds_read2_b64 v[38:41], v95 offset0:192 offset1:196
	ds_read2_b64 v[42:45], v96 offset0:224 offset1:228
	v_cmp_gt_f32_e32 vcc, s53, v19
	s_waitcnt lgkmcnt(6)
	v_mfma_f32_16x16x32_bf16 v[0:3], v[0:3], v[4:7], 0
	v_cvt_pk_bf16_f32 v89, v90, v91
	v_cndmask_b32_e32 v19, 0, v78, vcc
	v_fma_f32 v13, |v13|, v83, v19
	v_exp_f32_e32 v13, v13
	v_cndmask_b32_e32 v19, 0, v79, vcc
	s_waitcnt lgkmcnt(5)
	v_mfma_f32_16x16x32_bf16 v[8:11], v[8:11], v[4:7], 0
	v_cvt_pk_bf16_f32 v90, v22, v23
	v_ldexp_f32 v19, v13, v19
	v_pk_mul_f32 v[18:19], v[18:19], v[24:25]
	s_waitcnt lgkmcnt(4)
	v_mfma_f32_16x16x32_bf16 v[26:29], v[26:29], v[4:7], 0
	ds_read2_b64 v[22:25], v92 offset0:72 offset1:76
	v_cvt_pk_bf16_f32 v88, v46, v47
	v_cvt_pk_bf16_f32 v91, v18, v19
	s_waitcnt lgkmcnt(4)
	v_mfma_f32_16x16x32_bf16 v[30:33], v[30:33], v[4:7], 0
	v_ashrrev_i32_e32 v13, 31, v12
	v_lshlrev_b64 v[12:13], 15, v[12:13]
	v_lshlrev_b32_e32 v20, 8, v20
	s_waitcnt lgkmcnt(3)
	v_mfma_f32_16x16x32_bf16 v[84:87], v[14:17], v[4:7], 0
	ds_read2_b64 v[14:17], v75 offset0:8 offset1:12
	v_mov_b32_e32 v75, v65
	v_mov_b32_e32 v21, v65
	s_waitcnt lgkmcnt(3)
	v_mfma_f32_16x16x32_bf16 v[38:41], v[38:41], v[4:7], 0
	v_readlane_b32 s4, v255, 2
	v_readlane_b32 s6, v255, 4
	v_readlane_b32 s7, v255, 5
	s_waitcnt lgkmcnt(2)
	v_mfma_f32_16x16x32_bf16 v[42:45], v[42:45], v[4:7], 0
	ds_read2_b64 v[4:7], v77 offset0:40 offset1:44
	v_mov_b32_e32 v77, v65
	v_readlane_b32 s5, v255, 3
	s_waitcnt lgkmcnt(1)
	v_mfma_f32_16x16x32_bf16 v[16:19], v[14:17], v[88:91], v[0:3]
	v_readlane_b32 s8, v255, 6
	v_readlane_b32 s9, v255, 7
	v_readlane_b32 s10, v255, 8
	s_waitcnt lgkmcnt(0)
	v_mfma_f32_16x16x32_bf16 v[0:3], v[4:7], v[88:91], v[8:11]
	v_readlane_b32 s11, v255, 9
	s_nop 1
	ds_read2_b64 v[8:11], v93 offset0:104 offset1:108
	v_readlane_b32 s12, v255, 10
	v_mfma_f32_16x16x32_bf16 v[4:7], v[22:25], v[88:91], v[34:37]
	ds_read2_b64 v[22:25], v94 offset0:136 offset1:140
	v_readlane_b32 s13, v255, 11
	v_readlane_b32 s14, v255, 12
	s_waitcnt lgkmcnt(1)
	v_mfma_f32_16x16x32_bf16 v[8:11], v[8:11], v[88:91], v[26:29]
	s_nop 2
	v_lshl_add_u64 v[26:27], s[42:43], 0, v[12:13]
	v_lshl_add_u64 v[26:27], v[26:27], 0, v[74:75]
	v_lshl_add_u64 v[108:109], v[26:27], 0, v[20:21]
	s_waitcnt lgkmcnt(0)
	v_mfma_f32_16x16x32_bf16 v[12:15], v[22:25], v[88:91], v[30:33]
	ds_read2_b64 v[22:25], v69 offset0:168 offset1:172
	v_add_co_u32_e32 v134, vcc, s63, v108
	s_nop 1
	v_addc_co_u32_e32 v135, vcc, 0, v109, vcc
	v_add_co_u32_e32 v136, vcc, s64, v108
	s_nop 1
	v_addc_co_u32_e32 v137, vcc, 0, v109, vcc
	v_add_co_u32_e32 v138, vcc, s65, v108
	s_nop 1
	v_addc_co_u32_e32 v139, vcc, 0, v109, vcc
	v_add_co_u32_e32 v140, vcc, s66, v108
	s_nop 1
	v_addc_co_u32_e32 v141, vcc, 0, v109, vcc
	v_add_co_u32_e32 v142, vcc, s67, v108
	s_nop 1
	v_addc_co_u32_e32 v143, vcc, 0, v109, vcc
	v_add_co_u32_e32 v150, vcc, s68, v108
	s_nop 1
	v_addc_co_u32_e32 v151, vcc, 0, v109, vcc
	v_add_co_u32_e32 v152, vcc, s69, v108
	s_nop 1
	v_addc_co_u32_e32 v153, vcc, 0, v109, vcc
	global_load_dwordx4 v[160:163], v[108:109], off
	global_load_dwordx4 v[164:167], v[108:109], off offset:64
	global_load_dwordx4 v[168:171], v[108:109], off offset:128
	global_load_dwordx4 v[172:175], v[108:109], off offset:192
	global_load_dwordx4 v[176:179], v[134:135], off
	global_load_dwordx4 v[180:183], v[134:135], off offset:64
	global_load_dwordx4 v[184:187], v[134:135], off offset:128
	global_load_dwordx4 v[188:191], v[134:135], off offset:192
	global_load_dwordx4 v[192:195], v[136:137], off
	global_load_dwordx4 v[196:199], v[136:137], off offset:64
	global_load_dwordx4 v[200:203], v[136:137], off offset:128
	global_load_dwordx4 v[204:207], v[136:137], off offset:192
	global_load_dwordx4 v[208:211], v[138:139], off
	global_load_dwordx4 v[212:215], v[138:139], off offset:64
	global_load_dwordx4 v[216:219], v[138:139], off offset:128
	global_load_dwordx4 v[220:223], v[138:139], off offset:192
	global_load_dwordx4 v[224:227], v[140:141], off
	global_load_dwordx4 v[228:231], v[140:141], off offset:64
	global_load_dwordx4 v[232:235], v[140:141], off offset:128
	global_load_dwordx4 v[236:239], v[140:141], off offset:192
	global_load_dwordx4 v[240:243], v[142:143], off
	global_load_dwordx4 v[244:247], v[142:143], off offset:64
	global_load_dwordx4 v[248:251], v[142:143], off offset:128
	ds_read2_b64 v[30:33], v95 offset0:200 offset1:204
	s_waitcnt lgkmcnt(0)
	v_mfma_f32_16x16x32_bf16 v[20:23], v[22:25], v[88:91], v[84:87]
	v_ashrrev_i32_e32 v69, 31, v68
	v_mfma_f32_16x16x32_bf16 v[84:87], v[30:33], v[88:91], v[38:41]
	ds_read2_b64 v[30:33], v96 offset0:232 offset1:236
	s_waitcnt lgkmcnt(0)
	v_mfma_f32_16x16x32_bf16 v[88:91], v[30:33], v[88:91], v[42:45]
	s_nop 0
	s_waitcnt lgkmcnt(0)
	global_load_dwordx4 v[96:99], v[142:143], off offset:192
	global_load_dwordx4 v[100:103], v[150:151], off
	global_load_dwordx4 v[104:107], v[150:151], off offset:64
	s_waitcnt vmcnt(22)
	v_mfma_f32_16x16x32_bf16 v[36:39], v[160:163], v[56:59], 0
	v_mfma_f32_16x16x32_bf16 v[36:39], v[164:167], v[60:63], v[36:39]
	v_mfma_f32_16x16x32_bf16 v[36:39], v[168:171], v[52:55], v[36:39]
	v_mfma_f32_16x16x32_bf16 v[36:39], v[172:175], v[48:51], v[36:39]
	global_load_dwordx4 v[160:163], v[150:151], off offset:128
	global_load_dwordx4 v[164:167], v[150:151], off offset:192
	global_load_dwordx4 v[168:171], v[152:153], off
	global_load_dwordx4 v[172:175], v[152:153], off offset:64
	s_waitcnt vmcnt(22)
	v_mfma_f32_16x16x32_bf16 v[24:27], v[176:179], v[56:59], 0
	v_mfma_f32_16x16x32_bf16 v[24:27], v[180:183], v[60:63], v[24:27]
	v_mfma_f32_16x16x32_bf16 v[24:27], v[184:187], v[52:55], v[24:27]
	v_mfma_f32_16x16x32_bf16 v[24:27], v[188:191], v[48:51], v[24:27]
	global_load_dwordx4 v[176:179], v[152:153], off offset:128
	global_load_dwordx4 v[180:183], v[152:153], off offset:192
	s_waitcnt vmcnt(20)
	v_mfma_f32_16x16x32_bf16 v[28:31], v[192:195], v[56:59], 0
	v_mfma_f32_16x16x32_bf16 v[28:31], v[196:199], v[60:63], v[28:31]
	v_mfma_f32_16x16x32_bf16 v[28:31], v[200:203], v[52:55], v[28:31]
	v_mfma_f32_16x16x32_bf16 v[28:31], v[204:207], v[48:51], v[28:31]
	s_waitcnt vmcnt(16)
	v_mfma_f32_16x16x32_bf16 v[32:35], v[208:211], v[56:59], 0
	v_mfma_f32_16x16x32_bf16 v[32:35], v[212:215], v[60:63], v[32:35]
	v_mfma_f32_16x16x32_bf16 v[32:35], v[216:219], v[52:55], v[32:35]
	v_mfma_f32_16x16x32_bf16 v[32:35], v[220:223], v[48:51], v[32:35]
	s_waitcnt vmcnt(12)
	v_mfma_f32_16x16x32_bf16 v[40:43], v[224:227], v[56:59], 0
	v_mfma_f32_16x16x32_bf16 v[40:43], v[228:231], v[60:63], v[40:43]
	v_mfma_f32_16x16x32_bf16 v[40:43], v[232:235], v[52:55], v[40:43]
	v_mfma_f32_16x16x32_bf16 v[40:43], v[236:239], v[48:51], v[40:43]
	s_waitcnt vmcnt(8)
	v_mfma_f32_16x16x32_bf16 v[44:47], v[240:243], v[56:59], 0
	v_mfma_f32_16x16x32_bf16 v[44:47], v[244:247], v[60:63], v[44:47]
	v_mfma_f32_16x16x32_bf16 v[44:47], v[248:251], v[52:55], v[44:47]
	v_mfma_f32_16x16x32_bf16 v[44:47], v[96:99], v[48:51], v[44:47]
	s_waitcnt vmcnt(4)
	v_mfma_f32_16x16x32_bf16 v[92:95], v[100:103], v[56:59], 0
	v_mfma_f32_16x16x32_bf16 v[92:95], v[104:107], v[60:63], v[92:95]
	v_mfma_f32_16x16x32_bf16 v[92:95], v[160:163], v[52:55], v[92:95]
	v_mfma_f32_16x16x32_bf16 v[92:95], v[164:167], v[48:51], v[92:95]
	s_waitcnt vmcnt(0)
	v_mfma_f32_16x16x32_bf16 v[56:59], v[168:171], v[56:59], 0
	v_mfma_f32_16x16x32_bf16 v[56:59], v[172:175], v[60:63], v[56:59]
	v_mfma_f32_16x16x32_bf16 v[52:55], v[176:179], v[52:55], v[56:59]
	v_mfma_f32_16x16x32_bf16 v[48:51], v[180:183], v[48:51], v[52:55]
	v_readlane_b32 s15, v255, 13
	v_readlane_b32 s16, v255, 14
	v_readlane_b32 s17, v255, 15
	v_readlane_b32 s18, v255, 16
	v_readlane_b32 s19, v255, 17
	s_waitcnt lgkmcnt(0)
	s_nop 5
	s_waitcnt lgkmcnt(0)
	s_nop 2
	s_nop 2
	s_waitcnt lgkmcnt(0)
	s_nop 0
	s_nop 3
	s_waitcnt lgkmcnt(0)
	s_waitcnt lgkmcnt(0)
	s_waitcnt lgkmcnt(0)
	s_nop 0
	s_waitcnt lgkmcnt(0)
	s_nop 0
	s_waitcnt lgkmcnt(0)
	s_waitcnt lgkmcnt(0)
	s_nop 0
	s_waitcnt lgkmcnt(0)
	v_lshl_add_u64 v[100:101], v[68:69], 0, v[76:77]
	v_mad_u64_u32 v[60:61], s[0:1], v100, s57, v[66:67]
	v_mad_i32_i24 v61, v101, s57, v61
	v_lshl_add_u64 v[60:61], v[60:61], 0, v[72:73]
	v_lshl_add_u64 v[102:103], v[60:61], 0, v[64:65]
	v_add_co_u32_e32 v60, vcc, s63, v102
	s_waitcnt lgkmcnt(0)
	v_addc_co_u32_e32 v61, vcc, 0, v103, vcc
	v_mov_b64_e32 v[68:69], v[252:253]
	v_lshl_add_u64 v[232:233], v[102:103], 0, s[46:47]
	v_lshl_add_u64 v[234:235], v[70:71], 2, s[6:7]
	v_lshl_add_u64 v[234:235], v[234:235], 0, v[74:75]
	global_load_dwordx2 v[186:187], v[232:233], off offset:32
	global_load_dwordx2 v[188:189], v[232:233], off offset:64
	global_load_dwordx2 v[190:191], v[232:233], off offset:96
	global_load_dwordx2 v[192:193], v[232:233], off offset:128
	global_load_dwordx2 v[194:195], v[232:233], off offset:160
	global_load_dwordx2 v[196:197], v[232:233], off offset:192
	global_load_dwordx2 v[198:199], v[232:233], off offset:224
	global_load_dwordx4 v[204:207], v[234:235], off offset:64
	global_load_dwordx4 v[208:211], v[234:235], off offset:128
	global_load_dwordx4 v[212:215], v[234:235], off offset:192
	global_load_dwordx4 v[216:219], v[234:235], off offset:256
	global_load_dwordx4 v[220:223], v[234:235], off offset:320
	global_load_dwordx4 v[224:227], v[234:235], off offset:384
	global_load_dwordx4 v[228:231], v[234:235], off offset:448
	s_nop 0
	v_add_u32_e32 v56, 1, v76
	v_cvt_f32_ubyte0_e32 v56, v56
	v_mul_f32_e32 v57, v83, v56
	v_cmp_gt_f32_e32 vcc, s53, v57
	s_waitcnt vmcnt(0) lgkmcnt(0)
	v_lshlrev_b32_e32 v77, 16, v68
	v_cndmask_b32_e32 v57, 0, v78, vcc
	v_fmac_f32_e32 v57, v83, v56
	v_exp_f32_e32 v56, v57
	v_cndmask_b32_e32 v52, 0, v79, vcc
	v_and_b32_e32 v68, 0xffff0000, v68
	v_cmp_lt_i32_e32 vcc, v157, v156
	v_ldexp_f32 v62, v56, v52
	v_pk_fma_f32 v[58:59], v[62:63], v[50:51], v[90:91] op_sel_hi:[0,1,1]
	v_lshlrev_b64 v[50:51], 11, v[100:101]
	v_lshl_add_u64 v[50:51], s[30:31], 0, v[50:51]
	v_lshl_add_u64 v[52:53], v[50:51], 0, v[72:73]
	v_mul_f32_e32 v72, 0xbfb8aa3b, v77
	v_pk_fma_f32 v[54:55], v[62:63], v[92:93], v[84:85] op_sel_hi:[0,1,1]
	v_exp_f32_e32 v84, v72
	v_mul_f32_e32 v72, 0xbfb8aa3b, v68
	v_exp_f32_e32 v85, v72
	v_pk_fma_f32 v[60:61], v[62:63], v[48:49], v[88:89] op_sel_hi:[0,1,1]
	v_cndmask_b32_e32 v48, v155, v157, vcc
	v_cmp_lt_i32_e32 vcc, v158, v156
	v_lshlrev_b32_e32 v76, 2, v48
	v_pk_fma_f32 v[56:57], v[62:63], v[94:95], v[86:87] op_sel_hi:[0,1,1]
	v_cndmask_b32_e32 v48, v155, v158, vcc
	v_lshlrev_b32_e32 v63, 2, v48
	v_pk_fma_f32 v[18:19], v[62:63], v[38:39], v[18:19] op_sel_hi:[0,1,1]
	v_pk_add_f32 v[38:39], v[84:85], 1.0 op_sel_hi:[1,0]
	v_lshlrev_b32_e32 v83, 16, v69
	v_and_b32_e32 v86, 0xffff0000, v69
	v_div_scale_f32 v69, s[0:1], v39, v39, v68
	v_rcp_f32_e32 v84, v69
	v_pk_fma_f32 v[16:17], v[62:63], v[36:37], v[16:17] op_sel_hi:[0,1,1]
	v_add_f32_e32 v36, 0, v16
	v_add_f32_e32 v85, v17, v36
	v_fma_f32 v36, -v69, v84, 1.0
	v_fmac_f32_e32 v84, v36, v84
	v_div_scale_f32 v36, vcc, v68, v39, v68
	v_mul_f32_e32 v37, v36, v84
	v_fma_f32 v87, -v69, v37, v36
	v_fmac_f32_e32 v37, v87, v84
	v_div_scale_f32 v87, s[0:1], v38, v38, v77
	v_rcp_f32_e32 v88, v87
	v_fma_f32 v36, -v69, v37, v36
	v_div_fmas_f32 v36, v36, v84, v37
	v_div_fixup_f32 v37, v36, v39, v68
	v_fma_f32 v36, -v87, v88, 1.0
	v_fmac_f32_e32 v88, v36, v88
	v_div_scale_f32 v36, vcc, v77, v38, v77
	v_mul_f32_e32 v39, v36, v88
	v_fma_f32 v68, -v87, v39, v36
	v_fmac_f32_e32 v39, v68, v88
	v_fma_f32 v36, -v87, v39, v36
	v_div_fmas_f32 v36, v36, v88, v39
	v_div_fixup_f32 v36, v36, v38, v77
	v_add_f32_e32 v38, v18, v85
	v_add_f32_e32 v38, v19, v38
	v_pk_fma_f32 v[0:1], v[62:63], v[24:25], v[0:1] op_sel_hi:[0,1,1]
	v_add_f32_e32 v24, v38, v0
	v_pk_fma_f32 v[2:3], v[62:63], v[26:27], v[2:3] op_sel_hi:[0,1,1]
	v_add_f32_e32 v24, v1, v24
	v_add_f32_e32 v24, v2, v24
	v_add_f32_e32 v24, v3, v24
	v_pk_fma_f32 v[4:5], v[62:63], v[28:29], v[4:5] op_sel_hi:[0,1,1]
	v_add_f32_e32 v24, v24, v4
	v_pk_fma_f32 v[6:7], v[62:63], v[30:31], v[6:7] op_sel_hi:[0,1,1]
	v_add_f32_e32 v24, v5, v24
	v_add_f32_e32 v24, v6, v24
	v_add_f32_e32 v24, v7, v24
	v_pk_fma_f32 v[8:9], v[62:63], v[32:33], v[8:9] op_sel_hi:[0,1,1]
	v_add_f32_e32 v24, v24, v8
	v_pk_fma_f32 v[10:11], v[62:63], v[34:35], v[10:11] op_sel_hi:[0,1,1]
	v_add_f32_e32 v24, v9, v24
	v_add_f32_e32 v24, v10, v24
	v_add_f32_e32 v24, v11, v24
	v_pk_fma_f32 v[12:13], v[62:63], v[40:41], v[12:13] op_sel_hi:[0,1,1]
	v_add_f32_e32 v24, v24, v12
	v_pk_fma_f32 v[14:15], v[62:63], v[42:43], v[14:15] op_sel_hi:[0,1,1]
	v_add_f32_e32 v24, v13, v24
	v_lshl_add_u64 v[48:49], v[70:71], 2, s[6:7]
	v_add_f32_e32 v24, v14, v24
	v_lshl_add_u64 v[48:49], v[48:49], 0, v[74:75]
	v_add_f32_e32 v28, v15, v24
	v_pk_fma_f32 v[26:27], v[62:63], v[44:45], v[20:21] op_sel_hi:[0,1,1]
	global_load_dwordx4 v[72:75], v[48:49], off
	v_add_f32_e32 v20, v28, v26
	v_pk_fma_f32 v[24:25], v[62:63], v[46:47], v[22:23] op_sel_hi:[0,1,1]
	v_add_f32_e32 v20, v27, v20
	v_add_f32_e32 v20, v24, v20
	v_add_f32_e32 v20, v25, v20
	v_add_f32_e32 v20, v20, v54
	v_add_f32_e32 v20, v55, v20
	v_mul_f32_e32 v68, 0xbfb8aa3b, v83
	v_mul_f32_e32 v69, 0xbfb8aa3b, v86
	v_add_f32_e32 v20, v56, v20
	v_exp_f32_e32 v68, v68
	v_exp_f32_e32 v69, v69
	v_add_f32_e32 v20, v57, v20
	v_add_f32_e32 v20, v20, v60
	v_add_f32_e32 v20, v61, v20
	v_add_f32_e32 v20, v58, v20
	v_pk_add_f32 v[68:69], v[68:69], 1.0 op_sel_hi:[1,0]
	v_add_f32_e32 v20, v59, v20
	v_div_scale_f32 v39, s[0:1], v69, v69, v86
	ds_bpermute_b32 v21, v76, v20
	v_rcp_f32_e32 v84, v39
	v_lshl_add_u64 v[50:51], v[102:103], 0, s[46:47]
	v_fma_f32 v77, -v39, v84, 1.0
	s_waitcnt lgkmcnt(0)
	v_add_f32_e32 v20, v20, v21
	v_fmac_f32_e32 v84, v77, v84
	v_div_scale_f32 v77, vcc, v86, v69, v86
	ds_bpermute_b32 v21, v63, v20
	v_mul_f32_e32 v85, v77, v84
	v_fma_f32 v87, -v39, v85, v77
	v_fmac_f32_e32 v85, v87, v84
	v_fma_f32 v22, -v39, v85, v77
	v_div_fmas_f32 v22, v22, v84, v85
	s_waitcnt lgkmcnt(0)
	v_add_f32_e32 v20, v20, v21
	v_div_fixup_f32 v29, v22, v69, v86
	v_mul_f32_e32 v28, 0x3c000000, v20
	v_pk_add_f32 v[32:33], v[16:17], v[28:29] op_sel_hi:[1,0] neg_lo:[0,1] neg_hi:[0,1]
	v_pk_add_f32 v[38:39], v[18:19], v[28:29] op_sel_hi:[1,0] neg_lo:[0,1] neg_hi:[0,1]
	v_pk_mul_f32 v[34:35], v[32:33], v[32:33]
	v_pk_mul_f32 v[40:41], v[38:39], v[38:39]
	v_pk_add_f32 v[42:43], v[0:1], v[28:29] op_sel_hi:[1,0] neg_lo:[0,1] neg_hi:[0,1]
	v_pk_add_f32 v[46:47], v[2:3], v[28:29] op_sel_hi:[1,0] neg_lo:[0,1] neg_hi:[0,1]
	v_pk_add_f32 v[84:85], v[4:5], v[28:29] op_sel_hi:[1,0] neg_lo:[0,1] neg_hi:[0,1]
	v_pk_add_f32 v[88:89], v[6:7], v[28:29] op_sel_hi:[1,0] neg_lo:[0,1] neg_hi:[0,1]
	v_pk_add_f32 v[22:23], v[8:9], v[28:29] op_sel_hi:[1,0] neg_lo:[0,1] neg_hi:[0,1]
	v_pk_add_f32 v[20:21], v[10:11], v[28:29] op_sel_hi:[1,0] neg_lo:[0,1] neg_hi:[0,1]
	v_pk_add_f32 v[18:19], v[12:13], v[28:29] op_sel_hi:[1,0] neg_lo:[0,1] neg_hi:[0,1]
	v_pk_add_f32 v[16:17], v[14:15], v[28:29] op_sel_hi:[1,0] neg_lo:[0,1] neg_hi:[0,1]
	v_pk_add_f32 v[14:15], v[26:27], v[28:29] op_sel_hi:[1,0] neg_lo:[0,1] neg_hi:[0,1]
	v_pk_add_f32 v[12:13], v[24:25], v[28:29] op_sel_hi:[1,0] neg_lo:[0,1] neg_hi:[0,1]
	v_pk_add_f32 v[4:5], v[60:61], v[28:29] op_sel_hi:[1,0] neg_lo:[0,1] neg_hi:[0,1]
	v_pk_add_f32 v[0:1], v[58:59], v[28:29] op_sel_hi:[1,0] neg_lo:[0,1] neg_hi:[0,1]
	v_pk_add_f32 v[8:9], v[56:57], v[28:29] op_sel_hi:[1,0] neg_lo:[0,1] neg_hi:[0,1]
	v_pk_add_f32 v[10:11], v[54:55], v[28:29] op_sel_hi:[1,0] neg_lo:[0,1] neg_hi:[0,1]
	v_add_f32_e32 v28, v34, v35
	v_add_f32_e32 v28, v40, v28
	v_pk_mul_f32 v[44:45], v[42:43], v[42:43]
	v_add_f32_e32 v28, v41, v28
	v_add_f32_e32 v28, v44, v28
	v_pk_mul_f32 v[2:3], v[46:47], v[46:47]
	v_add_f32_e32 v28, v45, v28
	v_add_f32_e32 v2, v2, v28
	v_pk_mul_f32 v[86:87], v[84:85], v[84:85]
	v_add_f32_e32 v2, v3, v2
	v_add_f32_e32 v2, v86, v2
	v_pk_mul_f32 v[6:7], v[88:89], v[88:89]
	v_add_f32_e32 v2, v87, v2
	v_add_f32_e32 v2, v6, v2
	v_pk_mul_f32 v[90:91], v[22:23], v[22:23]
	v_add_f32_e32 v2, v7, v2
	v_add_f32_e32 v2, v90, v2
	v_pk_mul_f32 v[92:93], v[20:21], v[20:21]
	v_add_f32_e32 v2, v91, v2
	v_add_f32_e32 v2, v92, v2
	v_pk_mul_f32 v[94:95], v[18:19], v[18:19]
	v_add_f32_e32 v2, v93, v2
	v_add_f32_e32 v2, v94, v2
	v_pk_mul_f32 v[96:97], v[16:17], v[16:17]
	v_add_f32_e32 v2, v95, v2
	v_add_f32_e32 v2, v96, v2
	v_pk_mul_f32 v[26:27], v[14:15], v[14:15]
	v_add_f32_e32 v2, v97, v2
	v_add_f32_e32 v2, v26, v2
	v_pk_mul_f32 v[24:25], v[12:13], v[12:13]
	v_add_f32_e32 v2, v27, v2
	v_add_f32_e32 v2, v24, v2
	v_pk_mul_f32 v[54:55], v[10:11], v[10:11]
	v_add_f32_e32 v2, v25, v2
	v_add_f32_e32 v2, v54, v2
	v_pk_mul_f32 v[56:57], v[8:9], v[8:9]
	v_add_f32_e32 v2, v55, v2
	v_add_f32_e32 v2, v56, v2
	v_pk_mul_f32 v[60:61], v[4:5], v[4:5]
	v_add_f32_e32 v2, v57, v2
	v_add_f32_e32 v2, v60, v2
	v_pk_mul_f32 v[58:59], v[0:1], v[0:1]
	v_add_f32_e32 v2, v61, v2
	v_add_f32_e32 v2, v58, v2
	v_add_f32_e32 v2, v59, v2
	ds_bpermute_b32 v3, v76, v2
	v_div_scale_f32 v62, s[0:1], v68, v68, v83
	v_rcp_f32_e32 v69, v62
	s_waitcnt vmcnt(0)
	v_lshlrev_b32_e32 v40, 16, v31
	s_waitcnt lgkmcnt(0)
	v_add_f32_e32 v2, v2, v3
	ds_bpermute_b32 v3, v63, v2
	v_fma_f32 v6, -v62, v69, 1.0
	v_fmac_f32_e32 v69, v6, v69
	v_div_scale_f32 v6, vcc, v83, v68, v83
	s_waitcnt lgkmcnt(0)
	v_add_f32_e32 v2, v2, v3
	v_fmamk_f32 v2, v2, 0x3c000000, v81
	v_mul_f32_e32 v7, v6, v69
	v_mul_f32_e32 v3, 0x4b800000, v2
	v_cmp_gt_f32_e64 s[0:1], s54, v2
	v_fma_f32 v24, -v62, v7, v6
	v_fmac_f32_e32 v7, v24, v69
	v_cndmask_b32_e64 v2, v2, v3, s[0:1]
	v_rsq_f32_e32 v24, v2
	v_fma_f32 v6, -v62, v7, v6
	v_div_fmas_f32 v2, v6, v69, v7
	v_div_fixup_f32 v28, v2, v68, v83
	v_mul_f32_e32 v6, 0x45800000, v24
	v_cndmask_b32_e64 v6, v24, v6, s[0:1]
	v_pk_mul_f32 v[24:25], v[32:33], v[6:7] op_sel_hi:[1,0]
	v_pk_mul_f32 v[26:27], v[38:39], v[6:7] op_sel_hi:[1,0]
	v_pk_mul_f32 v[24:25], v[72:73], v[24:25]
	v_pk_mul_f32 v[26:27], v[74:75], v[26:27]
	v_pk_mul_f32 v[24:25], v[36:37], v[24:25]
	v_pk_mul_f32 v[26:27], v[28:29], v[26:27]
	v_lshl_add_u64 v[2:3], v[52:53], 0, v[64:65]
	v_bfe_u32 v180, v154, 4, 2
	v_lshlrev_b32_e32 v180, 3, v180
	v_mov_b32_e32 v181, 0
	v_lshl_add_u64 v[180:181], v[2:3], 0, v[180:181]
	v_cvt_pk_bf16_f32 v24, v24, v25
	v_cvt_pk_bf16_f32 v25, v26, v27
	v_lshlrev_b32_e32 v32, 16, v186
	v_and_b32_e32 v33, 0xffff0000, v186
	v_lshlrev_b32_e32 v34, 16, v187
	v_and_b32_e32 v35, 0xffff0000, v187
	v_mul_f32_e32 v36, 0xbfb8aa3b, v32
	v_mul_f32_e32 v37, 0xbfb8aa3b, v33
	v_mul_f32_e32 v38, 0xbfb8aa3b, v34
	v_mul_f32_e32 v39, 0xbfb8aa3b, v35
	v_exp_f32_e32 v36, v36
	v_exp_f32_e32 v37, v37
	v_exp_f32_e32 v38, v38
	v_exp_f32_e32 v39, v39
	v_pk_mul_f32 v[42:43], v[42:43], v[6:7] op_sel_hi:[1,0]
	v_pk_mul_f32 v[46:47], v[46:47], v[6:7] op_sel_hi:[1,0]
	v_pk_add_f32 v[36:37], v[36:37], 1.0 op_sel_hi:[1,0]
	v_pk_add_f32 v[38:39], v[38:39], 1.0 op_sel_hi:[1,0]
	v_pk_mul_f32 v[42:43], v[204:205], v[42:43]
	v_pk_mul_f32 v[46:47], v[206:207], v[46:47]
	v_rcp_f32_e32 v36, v36
	v_rcp_f32_e32 v37, v37
	v_rcp_f32_e32 v38, v38
	v_rcp_f32_e32 v39, v39
	v_pk_mul_f32 v[32:33], v[32:33], v[36:37]
	v_pk_mul_f32 v[34:35], v[34:35], v[38:39]
	v_pk_mul_f32 v[42:43], v[32:33], v[42:43]
	v_pk_mul_f32 v[46:47], v[34:35], v[46:47]
	v_cvt_pk_bf16_f32 v26, v42, v43
	v_cvt_pk_bf16_f32 v27, v46, v47
	s_nop 1
	v_permlane32_swap_b32_e32 v24, v26
	v_permlane32_swap_b32_e32 v25, v27
	s_nop 0
	v_permlane16_swap_b32_e32 v24, v26
	v_permlane16_swap_b32_e32 v25, v27
	global_store_dwordx4 v[180:181], v[24:27], off
	v_lshlrev_b32_e32 v172, 16, v188
	v_and_b32_e32 v173, 0xffff0000, v188
	v_lshlrev_b32_e32 v174, 16, v189
	v_and_b32_e32 v175, 0xffff0000, v189
	v_mul_f32_e32 v176, 0xbfb8aa3b, v172
	v_mul_f32_e32 v177, 0xbfb8aa3b, v173
	v_mul_f32_e32 v178, 0xbfb8aa3b, v174
	v_mul_f32_e32 v179, 0xbfb8aa3b, v175
	v_exp_f32_e32 v176, v176
	v_exp_f32_e32 v177, v177
	v_exp_f32_e32 v178, v178
	v_exp_f32_e32 v179, v179
	v_pk_mul_f32 v[84:85], v[84:85], v[6:7] op_sel_hi:[1,0]
	v_pk_mul_f32 v[88:89], v[88:89], v[6:7] op_sel_hi:[1,0]
	v_pk_add_f32 v[176:177], v[176:177], 1.0 op_sel_hi:[1,0]
	v_pk_add_f32 v[178:179], v[178:179], 1.0 op_sel_hi:[1,0]
	v_pk_mul_f32 v[84:85], v[208:209], v[84:85]
	v_pk_mul_f32 v[88:89], v[210:211], v[88:89]
	v_rcp_f32_e32 v176, v176
	v_rcp_f32_e32 v177, v177
	v_rcp_f32_e32 v178, v178
	v_rcp_f32_e32 v179, v179
	v_pk_mul_f32 v[172:173], v[172:173], v[176:177]
	v_pk_mul_f32 v[174:175], v[174:175], v[178:179]
	v_pk_mul_f32 v[84:85], v[172:173], v[84:85]
	v_pk_mul_f32 v[88:89], v[174:175], v[88:89]
	v_cvt_pk_bf16_f32 v160, v84, v85
	v_cvt_pk_bf16_f32 v161, v88, v89
	v_lshlrev_b32_e32 v32, 16, v190
	v_and_b32_e32 v33, 0xffff0000, v190
	v_lshlrev_b32_e32 v34, 16, v191
	v_and_b32_e32 v35, 0xffff0000, v191
	v_mul_f32_e32 v36, 0xbfb8aa3b, v32
	v_mul_f32_e32 v37, 0xbfb8aa3b, v33
	v_mul_f32_e32 v38, 0xbfb8aa3b, v34
	v_mul_f32_e32 v39, 0xbfb8aa3b, v35
	v_exp_f32_e32 v36, v36
	v_exp_f32_e32 v37, v37
	v_exp_f32_e32 v38, v38
	v_exp_f32_e32 v39, v39
	v_pk_mul_f32 v[22:23], v[22:23], v[6:7] op_sel_hi:[1,0]
	v_pk_mul_f32 v[20:21], v[20:21], v[6:7] op_sel_hi:[1,0]
	v_pk_add_f32 v[36:37], v[36:37], 1.0 op_sel_hi:[1,0]
	v_pk_add_f32 v[38:39], v[38:39], 1.0 op_sel_hi:[1,0]
	v_pk_mul_f32 v[22:23], v[212:213], v[22:23]
	v_pk_mul_f32 v[20:21], v[214:215], v[20:21]
	v_rcp_f32_e32 v36, v36
	v_rcp_f32_e32 v37, v37
	v_rcp_f32_e32 v38, v38
	v_rcp_f32_e32 v39, v39
	v_pk_mul_f32 v[32:33], v[32:33], v[36:37]
	v_pk_mul_f32 v[34:35], v[34:35], v[38:39]
	v_pk_mul_f32 v[22:23], v[32:33], v[22:23]
	v_pk_mul_f32 v[20:21], v[34:35], v[20:21]
	v_cvt_pk_bf16_f32 v162, v22, v23
	v_cvt_pk_bf16_f32 v163, v20, v21
	s_nop 1
	v_permlane32_swap_b32_e32 v160, v162
	v_permlane32_swap_b32_e32 v161, v163
	s_nop 0
	v_permlane16_swap_b32_e32 v160, v162
	v_permlane16_swap_b32_e32 v161, v163
	global_store_dwordx4 v[180:181], v[160:163], off offset:64
	v_lshlrev_b32_e32 v172, 16, v192
	v_and_b32_e32 v173, 0xffff0000, v192
	v_lshlrev_b32_e32 v174, 16, v193
	v_and_b32_e32 v175, 0xffff0000, v193
	v_mul_f32_e32 v176, 0xbfb8aa3b, v172
	v_mul_f32_e32 v177, 0xbfb8aa3b, v173
	v_mul_f32_e32 v178, 0xbfb8aa3b, v174
	v_mul_f32_e32 v179, 0xbfb8aa3b, v175
	v_exp_f32_e32 v176, v176
	v_exp_f32_e32 v177, v177
	v_exp_f32_e32 v178, v178
	v_exp_f32_e32 v179, v179
	v_pk_mul_f32 v[18:19], v[18:19], v[6:7] op_sel_hi:[1,0]
	v_pk_mul_f32 v[16:17], v[16:17], v[6:7] op_sel_hi:[1,0]
	v_pk_add_f32 v[176:177], v[176:177], 1.0 op_sel_hi:[1,0]
	v_pk_add_f32 v[178:179], v[178:179], 1.0 op_sel_hi:[1,0]
	v_pk_mul_f32 v[18:19], v[216:217], v[18:19]
	v_pk_mul_f32 v[16:17], v[218:219], v[16:17]
	v_rcp_f32_e32 v176, v176
	v_rcp_f32_e32 v177, v177
	v_rcp_f32_e32 v178, v178
	v_rcp_f32_e32 v179, v179
	v_pk_mul_f32 v[172:173], v[172:173], v[176:177]
	v_pk_mul_f32 v[174:175], v[174:175], v[178:179]
	v_pk_mul_f32 v[18:19], v[172:173], v[18:19]
	v_pk_mul_f32 v[16:17], v[174:175], v[16:17]
	v_cvt_pk_bf16_f32 v164, v18, v19
	v_cvt_pk_bf16_f32 v165, v16, v17
	v_lshlrev_b32_e32 v32, 16, v194
	v_and_b32_e32 v33, 0xffff0000, v194
	v_lshlrev_b32_e32 v34, 16, v195
	v_and_b32_e32 v35, 0xffff0000, v195
	v_mul_f32_e32 v36, 0xbfb8aa3b, v32
	v_mul_f32_e32 v37, 0xbfb8aa3b, v33
	v_mul_f32_e32 v38, 0xbfb8aa3b, v34
	v_mul_f32_e32 v39, 0xbfb8aa3b, v35
	v_exp_f32_e32 v36, v36
	v_exp_f32_e32 v37, v37
	v_exp_f32_e32 v38, v38
	v_exp_f32_e32 v39, v39
	v_pk_mul_f32 v[14:15], v[14:15], v[6:7] op_sel_hi:[1,0]
	v_pk_mul_f32 v[12:13], v[12:13], v[6:7] op_sel_hi:[1,0]
	v_pk_add_f32 v[36:37], v[36:37], 1.0 op_sel_hi:[1,0]
	v_pk_add_f32 v[38:39], v[38:39], 1.0 op_sel_hi:[1,0]
	v_pk_mul_f32 v[14:15], v[220:221], v[14:15]
	v_pk_mul_f32 v[12:13], v[222:223], v[12:13]
	v_rcp_f32_e32 v36, v36
	v_rcp_f32_e32 v37, v37
	v_rcp_f32_e32 v38, v38
	v_rcp_f32_e32 v39, v39
	v_pk_mul_f32 v[32:33], v[32:33], v[36:37]
	v_pk_mul_f32 v[34:35], v[34:35], v[38:39]
	v_pk_mul_f32 v[14:15], v[32:33], v[14:15]
	v_pk_mul_f32 v[12:13], v[34:35], v[12:13]
	v_cvt_pk_bf16_f32 v166, v14, v15
	v_cvt_pk_bf16_f32 v167, v12, v13
	s_nop 1
	v_permlane32_swap_b32_e32 v164, v166
	v_permlane32_swap_b32_e32 v165, v167
	s_nop 0
	v_permlane16_swap_b32_e32 v164, v166
	v_permlane16_swap_b32_e32 v165, v167
	global_store_dwordx4 v[180:181], v[164:167], off offset:128
	v_lshlrev_b32_e32 v172, 16, v196
	v_and_b32_e32 v173, 0xffff0000, v196
	v_lshlrev_b32_e32 v174, 16, v197
	v_and_b32_e32 v175, 0xffff0000, v197
	v_mul_f32_e32 v176, 0xbfb8aa3b, v172
	v_mul_f32_e32 v177, 0xbfb8aa3b, v173
	v_mul_f32_e32 v178, 0xbfb8aa3b, v174
	v_mul_f32_e32 v179, 0xbfb8aa3b, v175
	v_exp_f32_e32 v176, v176
	v_exp_f32_e32 v177, v177
	v_exp_f32_e32 v178, v178
	v_exp_f32_e32 v179, v179
	v_pk_mul_f32 v[10:11], v[10:11], v[6:7] op_sel_hi:[1,0]
	v_pk_mul_f32 v[8:9], v[8:9], v[6:7] op_sel_hi:[1,0]
	v_pk_add_f32 v[176:177], v[176:177], 1.0 op_sel_hi:[1,0]
	v_pk_add_f32 v[178:179], v[178:179], 1.0 op_sel_hi:[1,0]
	v_pk_mul_f32 v[10:11], v[224:225], v[10:11]
	v_pk_mul_f32 v[8:9], v[226:227], v[8:9]
	v_rcp_f32_e32 v176, v176
	v_rcp_f32_e32 v177, v177
	v_rcp_f32_e32 v178, v178
	v_rcp_f32_e32 v179, v179
	v_pk_mul_f32 v[172:173], v[172:173], v[176:177]
	v_pk_mul_f32 v[174:175], v[174:175], v[178:179]
	v_pk_mul_f32 v[10:11], v[172:173], v[10:11]
	v_pk_mul_f32 v[8:9], v[174:175], v[8:9]
	v_cvt_pk_bf16_f32 v168, v10, v11
	v_cvt_pk_bf16_f32 v169, v8, v9
	v_lshlrev_b32_e32 v32, 16, v198
	v_and_b32_e32 v33, 0xffff0000, v198
	v_lshlrev_b32_e32 v34, 16, v199
	v_and_b32_e32 v35, 0xffff0000, v199
	v_mul_f32_e32 v36, 0xbfb8aa3b, v32
	v_mul_f32_e32 v37, 0xbfb8aa3b, v33
	v_mul_f32_e32 v38, 0xbfb8aa3b, v34
	v_mul_f32_e32 v39, 0xbfb8aa3b, v35
	v_exp_f32_e32 v36, v36
	v_exp_f32_e32 v37, v37
	v_exp_f32_e32 v38, v38
	v_exp_f32_e32 v39, v39
	v_pk_mul_f32 v[4:5], v[4:5], v[6:7] op_sel_hi:[1,0]
	v_pk_mul_f32 v[0:1], v[0:1], v[6:7] op_sel_hi:[1,0]
	v_pk_add_f32 v[36:37], v[36:37], 1.0 op_sel_hi:[1,0]
	v_pk_add_f32 v[38:39], v[38:39], 1.0 op_sel_hi:[1,0]
	v_pk_mul_f32 v[4:5], v[228:229], v[4:5]
	v_pk_mul_f32 v[0:1], v[230:231], v[0:1]
	v_rcp_f32_e32 v36, v36
	v_rcp_f32_e32 v37, v37
	v_rcp_f32_e32 v38, v38
	v_rcp_f32_e32 v39, v39
	v_pk_mul_f32 v[32:33], v[32:33], v[36:37]
	v_pk_mul_f32 v[34:35], v[34:35], v[38:39]
	v_pk_mul_f32 v[4:5], v[32:33], v[4:5]
	v_pk_mul_f32 v[0:1], v[34:35], v[0:1]
	v_cvt_pk_bf16_f32 v170, v4, v5
	v_cvt_pk_bf16_f32 v171, v0, v1
	s_nop 1
	v_permlane32_swap_b32_e32 v168, v170
	v_permlane32_swap_b32_e32 v169, v171
	s_nop 0
	v_permlane16_swap_b32_e32 v168, v170
	v_permlane16_swap_b32_e32 v169, v171
	global_store_dwordx4 v[180:181], v[168:171], off offset:192
	s_waitcnt lgkmcnt(0)
	s_barrier
	s_cbranch_scc1 .LBB0_495
